# speedup vs baseline: 1.1059x; 1.0086x over previous
.LBB0_849:
	s_andn2_b64 vcc, exec, s[4:5]
	s_cbranch_vccnz .LBB0_888
	v_readlane_b32 s0, v236, 0
	s_cmpk_lg_u32 s0, 0x200
	s_cbranch_scc1 .Lln_orig
	v_readlane_b32 s17, v233, 24
	v_lshrrev_b32_e32 v89, 6, v93
	v_and_b32_e32 v90, 63, v93
	v_readfirstlane_b32 s19, v89
	v_lshlrev_b32_e32 v166, 5, v90
	v_add_u32_e32 v167, 0x1000, v166
	v_lshlrev_b32_e32 v168, 4, v90
	s_lshl_b32 s0, s2, 2
	s_add_u32 s19, s19, s0
	s_mul_i32 s19, s19, 18
	s_add_u32 s23, s19, 18
	s_mov_b32 s24, -1
	s_cmp_lt_i32 s17, 0
	s_cbranch_scc1 .Lln_nogb
	v_readlane_b32 s20, v236, 3
	v_readlane_b32 s21, v236, 4
	s_lshl_b32 s0, s17, 13
	s_add_u32 s20, s20, s0
	s_addc_u32 s21, s21, 0
	global_load_dwordx4 v[94:97], v166, s[20:21] offset:0
	global_load_dwordx4 v[98:101], v166, s[20:21] offset:16
	global_load_dwordx4 v[102:105], v166, s[20:21] offset:2048
	global_load_dwordx4 v[106:109], v166, s[20:21] offset:2064
	global_load_dwordx4 v[110:113], v167, s[20:21] offset:0
	global_load_dwordx4 v[114:117], v167, s[20:21] offset:16
	global_load_dwordx4 v[118:121], v167, s[20:21] offset:2048
	global_load_dwordx4 v[122:125], v167, s[20:21] offset:2064
	v_readlane_b32 s20, v236, 5
	v_readlane_b32 s21, v236, 6
	s_add_u32 s20, s20, s0
	s_addc_u32 s21, s21, 0
	global_load_dwordx4 v[126:129], v166, s[20:21] offset:0
	global_load_dwordx4 v[130:133], v166, s[20:21] offset:16
	global_load_dwordx4 v[134:137], v166, s[20:21] offset:2048
	global_load_dwordx4 v[138:141], v166, s[20:21] offset:2064
	global_load_dwordx4 v[142:145], v167, s[20:21] offset:0
	global_load_dwordx4 v[146:149], v167, s[20:21] offset:16
	global_load_dwordx4 v[150:153], v167, s[20:21] offset:2048
	global_load_dwordx4 v[154:157], v167, s[20:21] offset:2064
	v_readlane_b32 s4, v236, 43
	v_readlane_b32 s5, v236, 44
	s_lshl_b32 s0, s19, 13
	s_add_u32 s4, s4, s0
	s_addc_u32 s5, s5, 0
	global_load_dwordx4 v[0:3], v166, s[4:5] offset:0
	global_load_dwordx4 v[4:7], v166, s[4:5] offset:16
	global_load_dwordx4 v[8:11], v166, s[4:5] offset:2048
	global_load_dwordx4 v[12:15], v166, s[4:5] offset:2064
	global_load_dwordx4 v[16:19], v167, s[4:5] offset:0
	global_load_dwordx4 v[20:23], v167, s[4:5] offset:16
	global_load_dwordx4 v[24:27], v167, s[4:5] offset:2048
	global_load_dwordx4 v[28:31], v167, s[4:5] offset:2064
	s_waitcnt vmcnt(0)
	s_cmp_lt_i32 s17, 3
	s_cbranch_scc0 .Lln_row_c
.Lln_row_a:
	s_add_u32 s22, s19, 1
	s_cmp_lt_u32 s22, s23
	s_cbranch_scc0 .Lln_nopf_a
	v_readlane_b32 s4, v236, 43
	v_readlane_b32 s5, v236, 44
	s_lshl_b32 s0, s22, 13
	s_add_u32 s4, s4, s0
	s_addc_u32 s5, s5, 0
	global_load_dwordx4 v[32:35], v166, s[4:5] offset:0
	global_load_dwordx4 v[36:39], v166, s[4:5] offset:16
	global_load_dwordx4 v[40:43], v166, s[4:5] offset:2048
	global_load_dwordx4 v[44:47], v166, s[4:5] offset:2064
	global_load_dwordx4 v[48:51], v167, s[4:5] offset:0
	global_load_dwordx4 v[52:55], v167, s[4:5] offset:16
	global_load_dwordx4 v[56:59], v167, s[4:5] offset:2048
	global_load_dwordx4 v[60:63], v167, s[4:5] offset:2064
.Lln_nopf_a:
	v_add_f32_e32 v89, v0, v1
	v_add_f32_e32 v89, v89, v2
	v_add_f32_e32 v89, v89, v3
	v_add_f32_e32 v89, v89, v4
	v_add_f32_e32 v89, v89, v5
	v_add_f32_e32 v89, v89, v6
	v_add_f32_e32 v89, v89, v7
	v_add_f32_e32 v89, v89, v8
	v_add_f32_e32 v89, v89, v9
	v_add_f32_e32 v89, v89, v10
	v_add_f32_e32 v89, v89, v11
	v_add_f32_e32 v89, v89, v12
	v_add_f32_e32 v89, v89, v13
	v_add_f32_e32 v89, v89, v14
	v_add_f32_e32 v89, v89, v15
	v_add_f32_e32 v89, v89, v16
	v_add_f32_e32 v89, v89, v17
	v_add_f32_e32 v89, v89, v18
	v_add_f32_e32 v89, v89, v19
	v_add_f32_e32 v89, v89, v20
	v_add_f32_e32 v89, v89, v21
	v_add_f32_e32 v89, v89, v22
	v_add_f32_e32 v89, v89, v23
	v_add_f32_e32 v89, v89, v24
	v_add_f32_e32 v89, v89, v25
	v_add_f32_e32 v89, v89, v26
	v_add_f32_e32 v89, v89, v27
	v_add_f32_e32 v89, v89, v28
	v_add_f32_e32 v89, v89, v29
	v_add_f32_e32 v89, v89, v30
	v_add_f32_e32 v89, v89, v31
	s_nop 1
	v_add_f32_dpp v89, v89, v89 quad_perm:[1,0,3,2] row_mask:0xf bank_mask:0xf bound_ctrl:1
	s_nop 1
	v_add_f32_dpp v89, v89, v89 quad_perm:[2,3,0,1] row_mask:0xf bank_mask:0xf bound_ctrl:1
	s_nop 1
	v_add_f32_dpp v89, v89, v89 row_half_mirror row_mask:0xf bank_mask:0xf bound_ctrl:1
	s_nop 1
	v_add_f32_dpp v89, v89, v89 row_mirror row_mask:0xf bank_mask:0xf bound_ctrl:1
	s_nop 0
	v_readlane_b32 s0, v89, 0
	v_readlane_b32 s1, v89, 16
	v_readlane_b32 s10, v89, 32
	v_readlane_b32 s11, v89, 48
	s_nop 1
	v_mov_b32_e32 v90, s0
	v_add_f32_e32 v90, s1, v90
	v_add_f32_e32 v90, s10, v90
	v_add_f32_e32 v90, s11, v90
	v_mul_f32_e32 v90, 0x3a000000, v90
	v_sub_f32_e32 v0, v0, v90
	v_sub_f32_e32 v1, v1, v90
	v_sub_f32_e32 v2, v2, v90
	v_sub_f32_e32 v3, v3, v90
	v_sub_f32_e32 v4, v4, v90
	v_sub_f32_e32 v5, v5, v90
	v_sub_f32_e32 v6, v6, v90
	v_sub_f32_e32 v7, v7, v90
	v_sub_f32_e32 v8, v8, v90
	v_sub_f32_e32 v9, v9, v90
	v_sub_f32_e32 v10, v10, v90
	v_sub_f32_e32 v11, v11, v90
	v_sub_f32_e32 v12, v12, v90
	v_sub_f32_e32 v13, v13, v90
	v_sub_f32_e32 v14, v14, v90
	v_sub_f32_e32 v15, v15, v90
	v_sub_f32_e32 v16, v16, v90
	v_sub_f32_e32 v17, v17, v90
	v_sub_f32_e32 v18, v18, v90
	v_sub_f32_e32 v19, v19, v90
	v_sub_f32_e32 v20, v20, v90
	v_sub_f32_e32 v21, v21, v90
	v_sub_f32_e32 v22, v22, v90
	v_sub_f32_e32 v23, v23, v90
	v_sub_f32_e32 v24, v24, v90
	v_sub_f32_e32 v25, v25, v90
	v_sub_f32_e32 v26, v26, v90
	v_sub_f32_e32 v27, v27, v90
	v_sub_f32_e32 v28, v28, v90
	v_sub_f32_e32 v29, v29, v90
	v_sub_f32_e32 v30, v30, v90
	v_sub_f32_e32 v31, v31, v90
	v_mul_f32_e32 v89, v0, v0
	v_fmac_f32_e32 v89, v1, v1
	v_fmac_f32_e32 v89, v2, v2
	v_fmac_f32_e32 v89, v3, v3
	v_fmac_f32_e32 v89, v4, v4
	v_fmac_f32_e32 v89, v5, v5
	v_fmac_f32_e32 v89, v6, v6
	v_fmac_f32_e32 v89, v7, v7
	v_fmac_f32_e32 v89, v8, v8
	v_fmac_f32_e32 v89, v9, v9
	v_fmac_f32_e32 v89, v10, v10
	v_fmac_f32_e32 v89, v11, v11
	v_fmac_f32_e32 v89, v12, v12
	v_fmac_f32_e32 v89, v13, v13
	v_fmac_f32_e32 v89, v14, v14
	v_fmac_f32_e32 v89, v15, v15
	v_fmac_f32_e32 v89, v16, v16
	v_fmac_f32_e32 v89, v17, v17
	v_fmac_f32_e32 v89, v18, v18
	v_fmac_f32_e32 v89, v19, v19
	v_fmac_f32_e32 v89, v20, v20
	v_fmac_f32_e32 v89, v21, v21
	v_fmac_f32_e32 v89, v22, v22
	v_fmac_f32_e32 v89, v23, v23
	v_fmac_f32_e32 v89, v24, v24
	v_fmac_f32_e32 v89, v25, v25
	v_fmac_f32_e32 v89, v26, v26
	v_fmac_f32_e32 v89, v27, v27
	v_fmac_f32_e32 v89, v28, v28
	v_fmac_f32_e32 v89, v29, v29
	v_fmac_f32_e32 v89, v30, v30
	v_fmac_f32_e32 v89, v31, v31
	s_nop 1
	v_add_f32_dpp v89, v89, v89 quad_perm:[1,0,3,2] row_mask:0xf bank_mask:0xf bound_ctrl:1
	s_nop 1
	v_add_f32_dpp v89, v89, v89 quad_perm:[2,3,0,1] row_mask:0xf bank_mask:0xf bound_ctrl:1
	s_nop 1
	v_add_f32_dpp v89, v89, v89 row_half_mirror row_mask:0xf bank_mask:0xf bound_ctrl:1
	s_nop 1
	v_add_f32_dpp v89, v89, v89 row_mirror row_mask:0xf bank_mask:0xf bound_ctrl:1
	s_nop 0
	v_readlane_b32 s0, v89, 0
	v_readlane_b32 s1, v89, 16
	v_readlane_b32 s10, v89, 32
	v_readlane_b32 s11, v89, 48
	s_nop 1
	v_mov_b32_e32 v90, s0
	v_add_f32_e32 v90, s1, v90
	v_add_f32_e32 v90, s10, v90
	v_add_f32_e32 v90, s11, v90
	v_mov_b32_e32 v195, 0x3727c5ac
	v_fmac_f32_e32 v195, 0x3a000000, v90
	v_rsq_f32_e32 v195, v195
	s_nop 0
	v_mul_f32_e32 v0, v0, v195
	v_mul_f32_e32 v1, v1, v195
	v_mul_f32_e32 v2, v2, v195
	v_mul_f32_e32 v3, v3, v195
	v_mul_f32_e32 v4, v4, v195
	v_mul_f32_e32 v5, v5, v195
	v_mul_f32_e32 v6, v6, v195
	v_mul_f32_e32 v7, v7, v195
	v_mul_f32_e32 v8, v8, v195
	v_mul_f32_e32 v9, v9, v195
	v_mul_f32_e32 v10, v10, v195
	v_mul_f32_e32 v11, v11, v195
	v_mul_f32_e32 v12, v12, v195
	v_mul_f32_e32 v13, v13, v195
	v_mul_f32_e32 v14, v14, v195
	v_mul_f32_e32 v15, v15, v195
	v_mul_f32_e32 v16, v16, v195
	v_mul_f32_e32 v17, v17, v195
	v_mul_f32_e32 v18, v18, v195
	v_mul_f32_e32 v19, v19, v195
	v_mul_f32_e32 v20, v20, v195
	v_mul_f32_e32 v21, v21, v195
	v_mul_f32_e32 v22, v22, v195
	v_mul_f32_e32 v23, v23, v195
	v_mul_f32_e32 v24, v24, v195
	v_mul_f32_e32 v25, v25, v195
	v_mul_f32_e32 v26, v26, v195
	v_mul_f32_e32 v27, v27, v195
	v_mul_f32_e32 v28, v28, v195
	v_mul_f32_e32 v29, v29, v195
	v_mul_f32_e32 v30, v30, v195
	v_mul_f32_e32 v31, v31, v195
	v_fma_f32 v0, v0, v94, v126
	v_fma_f32 v1, v1, v95, v127
	v_fma_f32 v2, v2, v96, v128
	v_fma_f32 v3, v3, v97, v129
	v_fma_f32 v4, v4, v98, v130
	v_fma_f32 v5, v5, v99, v131
	v_fma_f32 v6, v6, v100, v132
	v_fma_f32 v7, v7, v101, v133
	v_fma_f32 v8, v8, v102, v134
	v_fma_f32 v9, v9, v103, v135
	v_fma_f32 v10, v10, v104, v136
	v_fma_f32 v11, v11, v105, v137
	v_fma_f32 v12, v12, v106, v138
	v_fma_f32 v13, v13, v107, v139
	v_fma_f32 v14, v14, v108, v140
	v_fma_f32 v15, v15, v109, v141
	v_fma_f32 v16, v16, v110, v142
	v_fma_f32 v17, v17, v111, v143
	v_fma_f32 v18, v18, v112, v144
	v_fma_f32 v19, v19, v113, v145
	v_fma_f32 v20, v20, v114, v146
	v_fma_f32 v21, v21, v115, v147
	v_fma_f32 v22, v22, v116, v148
	v_fma_f32 v23, v23, v117, v149
	v_fma_f32 v24, v24, v118, v150
	v_fma_f32 v25, v25, v119, v151
	v_fma_f32 v26, v26, v120, v152
	v_fma_f32 v27, v27, v121, v153
	v_fma_f32 v28, v28, v122, v154
	v_fma_f32 v29, v29, v123, v155
	v_fma_f32 v30, v30, v124, v156
	v_fma_f32 v31, v31, v125, v157
	v_readlane_b32 s6, v236, 43
	v_readlane_b32 s7, v236, 44
	s_lshl_b32 s0, s19, 13
	s_add_u32 s6, s6, s0
	s_addc_u32 s7, s7, 0
	global_store_dwordx4 v166, v[0:3], s[6:7] offset:0
	global_store_dwordx4 v166, v[4:7], s[6:7] offset:16
	global_store_dwordx4 v166, v[8:11], s[6:7] offset:2048
	global_store_dwordx4 v166, v[12:15], s[6:7] offset:2064
	global_store_dwordx4 v167, v[16:19], s[6:7] offset:0
	global_store_dwordx4 v167, v[20:23], s[6:7] offset:16
	global_store_dwordx4 v167, v[24:27], s[6:7] offset:2048
	global_store_dwordx4 v167, v[28:31], s[6:7] offset:2064
	s_sub_u32 s0, s19, 0x1000
	s_lshr_b32 s0, s0, 12
	s_cmpk_lt_u32 s19, 0x1000
	s_cselect_b32 s0, 8, s0
	s_cmp_eq_u32 s0, s24
	s_cbranch_scc1 .Lln_pok_a
	s_mov_b32 s24, s0
	v_readlane_b32 s20, v235, 37
	v_readlane_b32 s21, v235, 38
	s_add_u32 s1, s17, 1
	s_mul_i32 s1, s1, 9
	s_add_u32 s1, s1, s0
	s_mul_i32 s1, s1, 0x6000
	s_add_u32 s20, s20, s1
	s_addc_u32 s21, s21, 0
	global_load_dwordx4 v[64:67], v166, s[20:21] offset:0
	global_load_dwordx4 v[68:71], v166, s[20:21] offset:16
	global_load_dwordx4 v[72:75], v166, s[20:21] offset:2048
	global_load_dwordx4 v[76:79], v166, s[20:21] offset:2064
	global_load_dwordx4 v[80:83], v167, s[20:21] offset:0
	global_load_dwordx4 v[84:87], v167, s[20:21] offset:16
	global_load_dwordx4 v[158:161], v167, s[20:21] offset:2048
	global_load_dwordx4 v[162:165], v167, s[20:21] offset:2064
	s_add_u32 s20, s20, 0x2000
	s_addc_u32 s21, s21, 0
	global_load_dwordx4 v[196:199], v166, s[20:21] offset:0
	global_load_dwordx4 v[200:203], v166, s[20:21] offset:16
	global_load_dwordx4 v[204:207], v166, s[20:21] offset:2048
	global_load_dwordx4 v[208:211], v166, s[20:21] offset:2064
	global_load_dwordx4 v[212:215], v167, s[20:21] offset:0
	global_load_dwordx4 v[216:219], v167, s[20:21] offset:16
	global_load_dwordx4 v[220:223], v167, s[20:21] offset:2048
	global_load_dwordx4 v[224:227], v167, s[20:21] offset:2064
	s_waitcnt vmcnt(0)
	v_add_f32_e32 v196, 1.0, v196
	v_add_f32_e32 v197, 1.0, v197
	v_add_f32_e32 v198, 1.0, v198
	v_add_f32_e32 v199, 1.0, v199
	v_add_f32_e32 v200, 1.0, v200
	v_add_f32_e32 v201, 1.0, v201
	v_add_f32_e32 v202, 1.0, v202
	v_add_f32_e32 v203, 1.0, v203
	v_add_f32_e32 v204, 1.0, v204
	v_add_f32_e32 v205, 1.0, v205
	v_add_f32_e32 v206, 1.0, v206
	v_add_f32_e32 v207, 1.0, v207
	v_add_f32_e32 v208, 1.0, v208
	v_add_f32_e32 v209, 1.0, v209
	v_add_f32_e32 v210, 1.0, v210
	v_add_f32_e32 v211, 1.0, v211
	v_add_f32_e32 v212, 1.0, v212
	v_add_f32_e32 v213, 1.0, v213
	v_add_f32_e32 v214, 1.0, v214
	v_add_f32_e32 v215, 1.0, v215
	v_add_f32_e32 v216, 1.0, v216
	v_add_f32_e32 v217, 1.0, v217
	v_add_f32_e32 v218, 1.0, v218
	v_add_f32_e32 v219, 1.0, v219
	v_add_f32_e32 v220, 1.0, v220
	v_add_f32_e32 v221, 1.0, v221
	v_add_f32_e32 v222, 1.0, v222
	v_add_f32_e32 v223, 1.0, v223
	v_add_f32_e32 v224, 1.0, v224
	v_add_f32_e32 v225, 1.0, v225
	v_add_f32_e32 v226, 1.0, v226
	v_add_f32_e32 v227, 1.0, v227
.Lln_pok_a:
	v_readlane_b32 s8, v236, 51
	v_readlane_b32 s9, v236, 52
	s_lshl_b32 s0, s19, 12
	s_add_u32 s8, s8, s0
	s_addc_u32 s9, s9, 0
	v_fma_f32 v89, v0, v196, v64
	v_fma_f32 v90, v1, v197, v65
	v_cvt_pk_bf16_f32 v170, v89, v90
	v_fma_f32 v89, v2, v198, v66
	v_fma_f32 v90, v3, v199, v67
	v_cvt_pk_bf16_f32 v171, v89, v90
	v_fma_f32 v89, v4, v200, v68
	v_fma_f32 v90, v5, v201, v69
	v_cvt_pk_bf16_f32 v172, v89, v90
	v_fma_f32 v89, v6, v202, v70
	v_fma_f32 v90, v7, v203, v71
	v_cvt_pk_bf16_f32 v173, v89, v90
	global_store_dwordx4 v168, v[170:173], s[8:9] offset:0
	v_fma_f32 v89, v8, v204, v72
	v_fma_f32 v90, v9, v205, v73
	v_cvt_pk_bf16_f32 v228, v89, v90
	v_fma_f32 v89, v10, v206, v74
	v_fma_f32 v90, v11, v207, v75
	v_cvt_pk_bf16_f32 v229, v89, v90
	v_fma_f32 v89, v12, v208, v76
	v_fma_f32 v90, v13, v209, v77
	v_cvt_pk_bf16_f32 v230, v89, v90
	v_fma_f32 v89, v14, v210, v78
	v_fma_f32 v90, v15, v211, v79
	v_cvt_pk_bf16_f32 v231, v89, v90
	global_store_dwordx4 v168, v[228:231], s[8:9] offset:1024
	v_fma_f32 v89, v16, v212, v80
	v_fma_f32 v90, v17, v213, v81
	v_cvt_pk_bf16_f32 v170, v89, v90
	v_fma_f32 v89, v18, v214, v82
	v_fma_f32 v90, v19, v215, v83
	v_cvt_pk_bf16_f32 v171, v89, v90
	v_fma_f32 v89, v20, v216, v84
	v_fma_f32 v90, v21, v217, v85
	v_cvt_pk_bf16_f32 v172, v89, v90
	v_fma_f32 v89, v22, v218, v86
	v_fma_f32 v90, v23, v219, v87
	v_cvt_pk_bf16_f32 v173, v89, v90
	global_store_dwordx4 v168, v[170:173], s[8:9] offset:2048
	v_fma_f32 v89, v24, v220, v158
	v_fma_f32 v90, v25, v221, v159
	v_cvt_pk_bf16_f32 v228, v89, v90
	v_fma_f32 v89, v26, v222, v160
	v_fma_f32 v90, v27, v223, v161
	v_cvt_pk_bf16_f32 v229, v89, v90
	v_fma_f32 v89, v28, v224, v162
	v_fma_f32 v90, v29, v225, v163
	v_cvt_pk_bf16_f32 v230, v89, v90
	v_fma_f32 v89, v30, v226, v164
	v_fma_f32 v90, v31, v227, v165
	v_cvt_pk_bf16_f32 v231, v89, v90
	global_store_dwordx4 v168, v[228:231], s[8:9] offset:3072
	s_add_u32 s19, s19, 1
	s_cmp_lt_u32 s19, s23
	s_cbranch_scc0 .Lln_done
	s_waitcnt vmcnt(12)
	v_mov_b32_e32 v0, v32
	v_mov_b32_e32 v1, v33
	v_mov_b32_e32 v2, v34
	v_mov_b32_e32 v3, v35
	v_mov_b32_e32 v4, v36
	v_mov_b32_e32 v5, v37
	v_mov_b32_e32 v6, v38
	v_mov_b32_e32 v7, v39
	v_mov_b32_e32 v8, v40
	v_mov_b32_e32 v9, v41
	v_mov_b32_e32 v10, v42
	v_mov_b32_e32 v11, v43
	v_mov_b32_e32 v12, v44
	v_mov_b32_e32 v13, v45
	v_mov_b32_e32 v14, v46
	v_mov_b32_e32 v15, v47
	v_mov_b32_e32 v16, v48
	v_mov_b32_e32 v17, v49
	v_mov_b32_e32 v18, v50
	v_mov_b32_e32 v19, v51
	v_mov_b32_e32 v20, v52
	v_mov_b32_e32 v21, v53
	v_mov_b32_e32 v22, v54
	v_mov_b32_e32 v23, v55
	v_mov_b32_e32 v24, v56
	v_mov_b32_e32 v25, v57
	v_mov_b32_e32 v26, v58
	v_mov_b32_e32 v27, v59
	v_mov_b32_e32 v28, v60
	v_mov_b32_e32 v29, v61
	v_mov_b32_e32 v30, v62
	v_mov_b32_e32 v31, v63
	s_branch .Lln_row_a

.Lln_nopf_c:
	v_add_f32_e32 v89, v0, v1
	v_add_f32_e32 v89, v89, v2
	v_add_f32_e32 v89, v89, v3
	v_add_f32_e32 v89, v89, v4
	v_add_f32_e32 v89, v89, v5
	v_add_f32_e32 v89, v89, v6
	v_add_f32_e32 v89, v89, v7
	v_add_f32_e32 v89, v89, v8
	v_add_f32_e32 v89, v89, v9
	v_add_f32_e32 v89, v89, v10
	v_add_f32_e32 v89, v89, v11
	v_add_f32_e32 v89, v89, v12
	v_add_f32_e32 v89, v89, v13
	v_add_f32_e32 v89, v89, v14
	v_add_f32_e32 v89, v89, v15
	v_add_f32_e32 v89, v89, v16
	v_add_f32_e32 v89, v89, v17
	v_add_f32_e32 v89, v89, v18
	v_add_f32_e32 v89, v89, v19
	v_add_f32_e32 v89, v89, v20
	v_add_f32_e32 v89, v89, v21
	v_add_f32_e32 v89, v89, v22
	v_add_f32_e32 v89, v89, v23
	v_add_f32_e32 v89, v89, v24
	v_add_f32_e32 v89, v89, v25
	v_add_f32_e32 v89, v89, v26
	v_add_f32_e32 v89, v89, v27
	v_add_f32_e32 v89, v89, v28
	v_add_f32_e32 v89, v89, v29
	v_add_f32_e32 v89, v89, v30
	v_add_f32_e32 v89, v89, v31
	s_nop 1
	v_add_f32_dpp v89, v89, v89 quad_perm:[1,0,3,2] row_mask:0xf bank_mask:0xf bound_ctrl:1
	s_nop 1
	v_add_f32_dpp v89, v89, v89 quad_perm:[2,3,0,1] row_mask:0xf bank_mask:0xf bound_ctrl:1
	s_nop 1
	v_add_f32_dpp v89, v89, v89 row_half_mirror row_mask:0xf bank_mask:0xf bound_ctrl:1
	s_nop 1
	v_add_f32_dpp v89, v89, v89 row_mirror row_mask:0xf bank_mask:0xf bound_ctrl:1
	s_nop 0
	v_readlane_b32 s0, v89, 0
	v_readlane_b32 s1, v89, 16
	v_readlane_b32 s10, v89, 32
	v_readlane_b32 s11, v89, 48
	s_nop 1
	v_mov_b32_e32 v90, s0
	v_add_f32_e32 v90, s1, v90
	v_add_f32_e32 v90, s10, v90
	v_add_f32_e32 v90, s11, v90
	v_mul_f32_e32 v90, 0x3a000000, v90
	v_sub_f32_e32 v0, v0, v90
	v_sub_f32_e32 v1, v1, v90
	v_sub_f32_e32 v2, v2, v90
	v_sub_f32_e32 v3, v3, v90
	v_sub_f32_e32 v4, v4, v90
	v_sub_f32_e32 v5, v5, v90
	v_sub_f32_e32 v6, v6, v90
	v_sub_f32_e32 v7, v7, v90
	v_sub_f32_e32 v8, v8, v90
	v_sub_f32_e32 v9, v9, v90
	v_sub_f32_e32 v10, v10, v90
	v_sub_f32_e32 v11, v11, v90
	v_sub_f32_e32 v12, v12, v90
	v_sub_f32_e32 v13, v13, v90
	v_sub_f32_e32 v14, v14, v90
	v_sub_f32_e32 v15, v15, v90
	v_sub_f32_e32 v16, v16, v90
	v_sub_f32_e32 v17, v17, v90
	v_sub_f32_e32 v18, v18, v90
	v_sub_f32_e32 v19, v19, v90
	v_sub_f32_e32 v20, v20, v90
	v_sub_f32_e32 v21, v21, v90
	v_sub_f32_e32 v22, v22, v90
	v_sub_f32_e32 v23, v23, v90
	v_sub_f32_e32 v24, v24, v90
	v_sub_f32_e32 v25, v25, v90
	v_sub_f32_e32 v26, v26, v90
	v_sub_f32_e32 v27, v27, v90
	v_sub_f32_e32 v28, v28, v90
	v_sub_f32_e32 v29, v29, v90
	v_sub_f32_e32 v30, v30, v90
	v_sub_f32_e32 v31, v31, v90
	v_mul_f32_e32 v89, v0, v0
	v_fmac_f32_e32 v89, v1, v1
	v_fmac_f32_e32 v89, v2, v2
	v_fmac_f32_e32 v89, v3, v3
	v_fmac_f32_e32 v89, v4, v4
	v_fmac_f32_e32 v89, v5, v5
	v_fmac_f32_e32 v89, v6, v6
	v_fmac_f32_e32 v89, v7, v7
	v_fmac_f32_e32 v89, v8, v8
	v_fmac_f32_e32 v89, v9, v9
	v_fmac_f32_e32 v89, v10, v10
	v_fmac_f32_e32 v89, v11, v11
	v_fmac_f32_e32 v89, v12, v12
	v_fmac_f32_e32 v89, v13, v13
	v_fmac_f32_e32 v89, v14, v14
	v_fmac_f32_e32 v89, v15, v15
	v_fmac_f32_e32 v89, v16, v16
	v_fmac_f32_e32 v89, v17, v17
	v_fmac_f32_e32 v89, v18, v18
	v_fmac_f32_e32 v89, v19, v19
	v_fmac_f32_e32 v89, v20, v20
	v_fmac_f32_e32 v89, v21, v21
	v_fmac_f32_e32 v89, v22, v22
	v_fmac_f32_e32 v89, v23, v23
	v_fmac_f32_e32 v89, v24, v24
	v_fmac_f32_e32 v89, v25, v25
	v_fmac_f32_e32 v89, v26, v26
	v_fmac_f32_e32 v89, v27, v27
	v_fmac_f32_e32 v89, v28, v28
	v_fmac_f32_e32 v89, v29, v29
	v_fmac_f32_e32 v89, v30, v30
	v_fmac_f32_e32 v89, v31, v31
	s_nop 1
	v_add_f32_dpp v89, v89, v89 quad_perm:[1,0,3,2] row_mask:0xf bank_mask:0xf bound_ctrl:1
	s_nop 1
	v_add_f32_dpp v89, v89, v89 quad_perm:[2,3,0,1] row_mask:0xf bank_mask:0xf bound_ctrl:1
	s_nop 1
	v_add_f32_dpp v89, v89, v89 row_half_mirror row_mask:0xf bank_mask:0xf bound_ctrl:1
	s_nop 1
	v_add_f32_dpp v89, v89, v89 row_mirror row_mask:0xf bank_mask:0xf bound_ctrl:1
	s_nop 0
	v_readlane_b32 s0, v89, 0
	v_readlane_b32 s1, v89, 16
	v_readlane_b32 s10, v89, 32
	v_readlane_b32 s11, v89, 48
	s_nop 1
	v_mov_b32_e32 v90, s0
	v_add_f32_e32 v90, s1, v90
	v_add_f32_e32 v90, s10, v90
	v_add_f32_e32 v90, s11, v90
	v_mov_b32_e32 v195, 0x3727c5ac
	v_fmac_f32_e32 v195, 0x3a000000, v90
	v_rsq_f32_e32 v195, v195
	s_nop 0
	v_mul_f32_e32 v0, v0, v195
	v_mul_f32_e32 v1, v1, v195
	v_mul_f32_e32 v2, v2, v195
	v_mul_f32_e32 v3, v3, v195
	v_mul_f32_e32 v4, v4, v195
	v_mul_f32_e32 v5, v5, v195
	v_mul_f32_e32 v6, v6, v195
	v_mul_f32_e32 v7, v7, v195
	v_mul_f32_e32 v8, v8, v195
	v_mul_f32_e32 v9, v9, v195
	v_mul_f32_e32 v10, v10, v195
	v_mul_f32_e32 v11, v11, v195
	v_mul_f32_e32 v12, v12, v195
	v_mul_f32_e32 v13, v13, v195
	v_mul_f32_e32 v14, v14, v195
	v_mul_f32_e32 v15, v15, v195
	v_mul_f32_e32 v16, v16, v195
	v_mul_f32_e32 v17, v17, v195
	v_mul_f32_e32 v18, v18, v195
	v_mul_f32_e32 v19, v19, v195
	v_mul_f32_e32 v20, v20, v195
	v_mul_f32_e32 v21, v21, v195
	v_mul_f32_e32 v22, v22, v195
	v_mul_f32_e32 v23, v23, v195
	v_mul_f32_e32 v24, v24, v195
	v_mul_f32_e32 v25, v25, v195
	v_mul_f32_e32 v26, v26, v195
	v_mul_f32_e32 v27, v27, v195
	v_mul_f32_e32 v28, v28, v195
	v_mul_f32_e32 v29, v29, v195
	v_mul_f32_e32 v30, v30, v195
	v_mul_f32_e32 v31, v31, v195
	v_fma_f32 v0, v0, v94, v126
	v_fma_f32 v1, v1, v95, v127
	v_fma_f32 v2, v2, v96, v128
	v_fma_f32 v3, v3, v97, v129
	v_fma_f32 v4, v4, v98, v130
	v_fma_f32 v5, v5, v99, v131
	v_fma_f32 v6, v6, v100, v132
	v_fma_f32 v7, v7, v101, v133
	v_fma_f32 v8, v8, v102, v134
	v_fma_f32 v9, v9, v103, v135
	v_fma_f32 v10, v10, v104, v136
	v_fma_f32 v11, v11, v105, v137
	v_fma_f32 v12, v12, v106, v138
	v_fma_f32 v13, v13, v107, v139
	v_fma_f32 v14, v14, v108, v140
	v_fma_f32 v15, v15, v109, v141
	v_fma_f32 v16, v16, v110, v142
	v_fma_f32 v17, v17, v111, v143
	v_fma_f32 v18, v18, v112, v144
	v_fma_f32 v19, v19, v113, v145
	v_fma_f32 v20, v20, v114, v146
	v_fma_f32 v21, v21, v115, v147
	v_fma_f32 v22, v22, v116, v148
	v_fma_f32 v23, v23, v117, v149
	v_fma_f32 v24, v24, v118, v150
	v_fma_f32 v25, v25, v119, v151
	v_fma_f32 v26, v26, v120, v152
	v_fma_f32 v27, v27, v121, v153
	v_fma_f32 v28, v28, v122, v154
	v_fma_f32 v29, v29, v123, v155
	v_fma_f32 v30, v30, v124, v156
	v_fma_f32 v31, v31, v125, v157
	v_readlane_b32 s6, v236, 43
	v_readlane_b32 s7, v236, 44
	s_lshl_b32 s0, s19, 13
	s_add_u32 s6, s6, s0
	s_addc_u32 s7, s7, 0
	global_store_dwordx4 v166, v[0:3], s[6:7] offset:0
	global_store_dwordx4 v166, v[4:7], s[6:7] offset:16
	global_store_dwordx4 v166, v[8:11], s[6:7] offset:2048
	global_store_dwordx4 v166, v[12:15], s[6:7] offset:2064
	global_store_dwordx4 v167, v[16:19], s[6:7] offset:0
	global_store_dwordx4 v167, v[20:23], s[6:7] offset:16
	global_store_dwordx4 v167, v[24:27], s[6:7] offset:2048
	global_store_dwordx4 v167, v[28:31], s[6:7] offset:2064
	s_add_u32 s19, s19, 1
	s_cmp_lt_u32 s19, s23
	s_cbranch_scc0 .Lln_done
	s_waitcnt vmcnt(8)
	v_mov_b32_e32 v0, v32
	v_mov_b32_e32 v1, v33
	v_mov_b32_e32 v2, v34
	v_mov_b32_e32 v3, v35
	v_mov_b32_e32 v4, v36
	v_mov_b32_e32 v5, v37
	v_mov_b32_e32 v6, v38
	v_mov_b32_e32 v7, v39
	v_mov_b32_e32 v8, v40
	v_mov_b32_e32 v9, v41
	v_mov_b32_e32 v10, v42
	v_mov_b32_e32 v11, v43
	v_mov_b32_e32 v12, v44
	v_mov_b32_e32 v13, v45
	v_mov_b32_e32 v14, v46
	v_mov_b32_e32 v15, v47
	v_mov_b32_e32 v16, v48
	v_mov_b32_e32 v17, v49
	v_mov_b32_e32 v18, v50
	v_mov_b32_e32 v19, v51
	v_mov_b32_e32 v20, v52
	v_mov_b32_e32 v21, v53
	v_mov_b32_e32 v22, v54
	v_mov_b32_e32 v23, v55
	v_mov_b32_e32 v24, v56
	v_mov_b32_e32 v25, v57
	v_mov_b32_e32 v26, v58
	v_mov_b32_e32 v27, v59
	v_mov_b32_e32 v28, v60
	v_mov_b32_e32 v29, v61
	v_mov_b32_e32 v30, v62
	v_mov_b32_e32 v31, v63
	s_branch .Lln_row_c
.Lln_nogb:
	v_readlane_b32 s4, v233, 3
	v_readlane_b32 s5, v233, 4
	v_readlane_b32 s10, v233, 5
	v_readlane_b32 s11, v233, 6
	s_sub_u32 s1, s19, 0x1000
	s_cmpk_lt_u32 s19, 0x1000
	s_cselect_b32 s0, s19, s1
	s_cselect_b32 s4, s4, s10
	s_cselect_b32 s5, s5, s11
	s_lshl_b32 s0, s0, 13
	s_add_u32 s4, s4, s0
	s_addc_u32 s5, s5, 0
	global_load_dwordx4 v[0:3], v166, s[4:5] offset:0
	global_load_dwordx4 v[4:7], v166, s[4:5] offset:16
	global_load_dwordx4 v[8:11], v166, s[4:5] offset:2048
	global_load_dwordx4 v[12:15], v166, s[4:5] offset:2064
	global_load_dwordx4 v[16:19], v167, s[4:5] offset:0
	global_load_dwordx4 v[20:23], v167, s[4:5] offset:16
	global_load_dwordx4 v[24:27], v167, s[4:5] offset:2048
	global_load_dwordx4 v[28:31], v167, s[4:5] offset:2064
	s_waitcnt vmcnt(0)
.Lln_row_b:
	s_add_u32 s22, s19, 1
	s_cmp_lt_u32 s22, s23
	s_cbranch_scc0 .Lln_nopf_b
	v_readlane_b32 s4, v233, 3
	v_readlane_b32 s5, v233, 4
	v_readlane_b32 s10, v233, 5
	v_readlane_b32 s11, v233, 6
	s_sub_u32 s1, s22, 0x1000
	s_cmpk_lt_u32 s22, 0x1000
	s_cselect_b32 s0, s22, s1
	s_cselect_b32 s4, s4, s10
	s_cselect_b32 s5, s5, s11
	s_lshl_b32 s0, s0, 13
	s_add_u32 s4, s4, s0
	s_addc_u32 s5, s5, 0
	global_load_dwordx4 v[32:35], v166, s[4:5] offset:0
	global_load_dwordx4 v[36:39], v166, s[4:5] offset:16
	global_load_dwordx4 v[40:43], v166, s[4:5] offset:2048
	global_load_dwordx4 v[44:47], v166, s[4:5] offset:2064
	global_load_dwordx4 v[48:51], v167, s[4:5] offset:0
	global_load_dwordx4 v[52:55], v167, s[4:5] offset:16
	global_load_dwordx4 v[56:59], v167, s[4:5] offset:2048
	global_load_dwordx4 v[60:63], v167, s[4:5] offset:2064
.Lln_nopf_b:
	s_sub_u32 s0, s19, 0x1000
	s_lshr_b32 s0, s0, 12
	s_cmpk_lt_u32 s19, 0x1000
	s_cselect_b32 s0, 8, s0
	s_cmp_eq_u32 s0, s24
	s_cbranch_scc1 .Lln_pok_b
	s_mov_b32 s24, s0
	v_readlane_b32 s20, v235, 37
	v_readlane_b32 s21, v235, 38
	s_add_u32 s1, s17, 1
	s_mul_i32 s1, s1, 9
	s_add_u32 s1, s1, s0
	s_mul_i32 s1, s1, 0x6000
	s_add_u32 s20, s20, s1
	s_addc_u32 s21, s21, 0
	global_load_dwordx4 v[64:67], v166, s[20:21] offset:0
	global_load_dwordx4 v[68:71], v166, s[20:21] offset:16
	global_load_dwordx4 v[72:75], v166, s[20:21] offset:2048
	global_load_dwordx4 v[76:79], v166, s[20:21] offset:2064
	global_load_dwordx4 v[80:83], v167, s[20:21] offset:0
	global_load_dwordx4 v[84:87], v167, s[20:21] offset:16
	global_load_dwordx4 v[158:161], v167, s[20:21] offset:2048
	global_load_dwordx4 v[162:165], v167, s[20:21] offset:2064
	s_add_u32 s20, s20, 0x2000
	s_addc_u32 s21, s21, 0
	global_load_dwordx4 v[196:199], v166, s[20:21] offset:0
	global_load_dwordx4 v[200:203], v166, s[20:21] offset:16
	global_load_dwordx4 v[204:207], v166, s[20:21] offset:2048
	global_load_dwordx4 v[208:211], v166, s[20:21] offset:2064
	global_load_dwordx4 v[212:215], v167, s[20:21] offset:0
	global_load_dwordx4 v[216:219], v167, s[20:21] offset:16
	global_load_dwordx4 v[220:223], v167, s[20:21] offset:2048
	global_load_dwordx4 v[224:227], v167, s[20:21] offset:2064
	s_waitcnt vmcnt(0)
	v_add_f32_e32 v196, 1.0, v196
	v_add_f32_e32 v197, 1.0, v197
	v_add_f32_e32 v198, 1.0, v198
	v_add_f32_e32 v199, 1.0, v199
	v_add_f32_e32 v200, 1.0, v200
	v_add_f32_e32 v201, 1.0, v201
	v_add_f32_e32 v202, 1.0, v202
	v_add_f32_e32 v203, 1.0, v203
	v_add_f32_e32 v204, 1.0, v204
	v_add_f32_e32 v205, 1.0, v205
	v_add_f32_e32 v206, 1.0, v206
	v_add_f32_e32 v207, 1.0, v207
	v_add_f32_e32 v208, 1.0, v208
	v_add_f32_e32 v209, 1.0, v209
	v_add_f32_e32 v210, 1.0, v210
	v_add_f32_e32 v211, 1.0, v211
	v_add_f32_e32 v212, 1.0, v212
	v_add_f32_e32 v213, 1.0, v213
	v_add_f32_e32 v214, 1.0, v214
	v_add_f32_e32 v215, 1.0, v215
	v_add_f32_e32 v216, 1.0, v216
	v_add_f32_e32 v217, 1.0, v217
	v_add_f32_e32 v218, 1.0, v218
	v_add_f32_e32 v219, 1.0, v219
	v_add_f32_e32 v220, 1.0, v220
	v_add_f32_e32 v221, 1.0, v221
	v_add_f32_e32 v222, 1.0, v222
	v_add_f32_e32 v223, 1.0, v223
	v_add_f32_e32 v224, 1.0, v224
	v_add_f32_e32 v225, 1.0, v225
	v_add_f32_e32 v226, 1.0, v226
	v_add_f32_e32 v227, 1.0, v227
.Lln_pok_b:
	v_readlane_b32 s8, v236, 51
	v_readlane_b32 s9, v236, 52
	s_lshl_b32 s0, s19, 12
	s_add_u32 s8, s8, s0
	s_addc_u32 s9, s9, 0
	v_fma_f32 v89, v0, v196, v64
	v_fma_f32 v90, v1, v197, v65
	v_cvt_pk_bf16_f32 v170, v89, v90
	v_fma_f32 v89, v2, v198, v66
	v_fma_f32 v90, v3, v199, v67
	v_cvt_pk_bf16_f32 v171, v89, v90
	v_fma_f32 v89, v4, v200, v68
	v_fma_f32 v90, v5, v201, v69
	v_cvt_pk_bf16_f32 v172, v89, v90
	v_fma_f32 v89, v6, v202, v70
	v_fma_f32 v90, v7, v203, v71
	v_cvt_pk_bf16_f32 v173, v89, v90
	global_store_dwordx4 v168, v[170:173], s[8:9] offset:0
	v_fma_f32 v89, v8, v204, v72
	v_fma_f32 v90, v9, v205, v73
	v_cvt_pk_bf16_f32 v228, v89, v90
	v_fma_f32 v89, v10, v206, v74
	v_fma_f32 v90, v11, v207, v75
	v_cvt_pk_bf16_f32 v229, v89, v90
	v_fma_f32 v89, v12, v208, v76
	v_fma_f32 v90, v13, v209, v77
	v_cvt_pk_bf16_f32 v230, v89, v90
	v_fma_f32 v89, v14, v210, v78
	v_fma_f32 v90, v15, v211, v79
	v_cvt_pk_bf16_f32 v231, v89, v90
	global_store_dwordx4 v168, v[228:231], s[8:9] offset:1024
	v_fma_f32 v89, v16, v212, v80
	v_fma_f32 v90, v17, v213, v81
	v_cvt_pk_bf16_f32 v170, v89, v90
	v_fma_f32 v89, v18, v214, v82
	v_fma_f32 v90, v19, v215, v83
	v_cvt_pk_bf16_f32 v171, v89, v90
	v_fma_f32 v89, v20, v216, v84
	v_fma_f32 v90, v21, v217, v85
	v_cvt_pk_bf16_f32 v172, v89, v90
	v_fma_f32 v89, v22, v218, v86
	v_fma_f32 v90, v23, v219, v87
	v_cvt_pk_bf16_f32 v173, v89, v90
	global_store_dwordx4 v168, v[170:173], s[8:9] offset:2048
	v_fma_f32 v89, v24, v220, v158
	v_fma_f32 v90, v25, v221, v159
	v_cvt_pk_bf16_f32 v228, v89, v90
	v_fma_f32 v89, v26, v222, v160
	v_fma_f32 v90, v27, v223, v161
	v_cvt_pk_bf16_f32 v229, v89, v90
	v_fma_f32 v89, v28, v224, v162
	v_fma_f32 v90, v29, v225, v163
	v_cvt_pk_bf16_f32 v230, v89, v90
	v_fma_f32 v89, v30, v226, v164
	v_fma_f32 v90, v31, v227, v165
	v_cvt_pk_bf16_f32 v231, v89, v90
	global_store_dwordx4 v168, v[228:231], s[8:9] offset:3072
	s_add_u32 s19, s19, 1
	s_cmp_lt_u32 s19, s23
	s_cbranch_scc0 .Lln_done
	s_waitcnt vmcnt(4)
	v_mov_b32_e32 v0, v32
	v_mov_b32_e32 v1, v33
	v_mov_b32_e32 v2, v34
	v_mov_b32_e32 v3, v35
	v_mov_b32_e32 v4, v36
	v_mov_b32_e32 v5, v37
	v_mov_b32_e32 v6, v38
	v_mov_b32_e32 v7, v39
	v_mov_b32_e32 v8, v40
	v_mov_b32_e32 v9, v41
	v_mov_b32_e32 v10, v42
	v_mov_b32_e32 v11, v43
	v_mov_b32_e32 v12, v44
	v_mov_b32_e32 v13, v45
	v_mov_b32_e32 v14, v46
	v_mov_b32_e32 v15, v47
	v_mov_b32_e32 v16, v48
	v_mov_b32_e32 v17, v49
	v_mov_b32_e32 v18, v50
	v_mov_b32_e32 v19, v51
	v_mov_b32_e32 v20, v52
	v_mov_b32_e32 v21, v53
	v_mov_b32_e32 v22, v54
	v_mov_b32_e32 v23, v55
	v_mov_b32_e32 v24, v56
	v_mov_b32_e32 v25, v57
	v_mov_b32_e32 v26, v58
	v_mov_b32_e32 v27, v59
	v_mov_b32_e32 v28, v60
	v_mov_b32_e32 v29, v61
	v_mov_b32_e32 v30, v62
	v_mov_b32_e32 v31, v63
	s_branch .Lln_row_b
.Lln_done:
	v_readlane_b32 s0, v233, 24
	v_mov_b32_e32 v28, v93
	s_add_i32 s36, s0, 1
	v_readlane_b32 s1, v234, 28
	v_readfirstlane_b32 s0, v28
	s_ashr_i32 s0, s0, 6
	s_add_i32 s12, s0, s1
	v_readlane_b32 s38, v234, 32
	v_readlane_b32 s40, v235, 62
	v_readlane_b32 s42, v234, 30
	v_readlane_b32 s44, v234, 34
	v_readlane_b32 s39, v234, 33
	v_readlane_b32 s41, v235, 63
	v_readlane_b32 s43, v234, 31
	v_readlane_b32 s45, v234, 35
	s_mov_b32 s37, 0x800000
	s_branch .LBB0_874
.Lln_orig:
	v_readlane_b32 s0, v233, 24
	v_mov_b32_e32 v28, v93
	s_add_i32 s36, s0, 1
	v_readlane_b32 s1, v234, 28
	v_readfirstlane_b32 s0, v28
	s_ashr_i32 s0, s0, 6
	s_add_i32 s12, s0, s1
	v_readlane_b32 s38, v234, 32
	v_readlane_b32 s40, v235, 62
	v_readlane_b32 s42, v234, 30
	v_readlane_b32 s44, v234, 34
	s_cmp_gt_i32 s12, 0x8fff
	v_readlane_b32 s39, v234, 33
	v_readlane_b32 s41, v235, 63
	v_readlane_b32 s43, v234, 31
	v_readlane_b32 s45, v234, 35
	s_mov_b32 s37, 0x800000
	s_cbranch_scc1 .LBB0_874
	v_readlane_b32 s1, v233, 24
	s_cmp_gt_i32 s1, -1
	s_cselect_b64 s[4:5], -1, 0
	s_cmp_lt_i32 s1, 0
	s_cselect_b64 s[6:7], -1, 0
	s_and_b64 vcc, exec, s[6:7]
	s_cbranch_vccz .LBB0_855
	s_cmpk_gt_i32 s12, 0xfff
	s_cbranch_scc0 .LBB0_856
	v_readlane_b32 s16, v233, 3
	s_add_i32 s40, s12, 0xfffff000
	v_readlane_b32 s18, v233, 5
	v_readlane_b32 s19, v233, 6
	s_ashr_i32 s13, s12, 31
	v_readlane_b32 s17, v233, 4
	v_readlane_b32 s20, v233, 7
	v_readlane_b32 s21, v233, 8
	v_readlane_b32 s22, v233, 9
	v_readlane_b32 s23, v233, 10
	v_readlane_b32 s24, v233, 11
	v_readlane_b32 s25, v233, 12
	v_readlane_b32 s26, v233, 13
	v_readlane_b32 s27, v233, 14
	v_readlane_b32 s28, v233, 15
	v_readlane_b32 s29, v233, 16
	v_readlane_b32 s30, v233, 17
	v_readlane_b32 s31, v233, 18
	s_mov_b64 s[10:11], s[18:19]
	s_mov_b64 s[14:15], s[40:41]
	s_cbranch_execz .LBB0_857
	s_branch .LBB0_858
